# XCD-local seams, no start stagger (XCD_SLEEP=0)
# baseline (speedup 1.0000x reference)
.Lxl_stag_loop:
	s_add_i32 s101, s101, -1
	s_cmp_lg_u32 s101, 0
	s_cbranch_scc1 .Lxl_stag_loop
